# attn_a: batch-per-XCD locality unit map (adjacent idx on a CU's two half-blocks)
# speedup vs baseline: 1.3267x; 1.0055x over previous
; DI void phase_attn_a(int wv_, int vb_, int nvb_, char* ws_, const Ctx& p, char* smem) {
;     ...
;   const int tid = tidx(wv_), lane = tid & 63, wave = tid >> 6, c = lane & 31, h = lane >> 5;
;   for (int k_ = 0; k_ < (6144 + nvb_ - 1) / nvb_; ++k_) {
;     const int u = (vb_ + k_ * nvb_ < 6144) ? vb_ + k_ * nvb_ : 6143;
;     const int head = u & 7, g = (u >> 3) % 3, rest = u / 24, idx = rest & 31, b = rest >> 5;
;     const int dil = (g == 0) ? 1 : ((g == 1) ? 4 : 16);
;     const int nbper = 32 / dil, r = idx / nbper, nb = idx % nbper;
;     u16* Og = (g == 0) ? (u16*)(ws_ + WS_H) : ((g == 1) ? (u16*)(ws_ + WS_H + 32 * MiB) : (u16*)(ws_ + WS_E));
;     float* lse = (float*)(ws_ + WS_LSE) + (size_t)g * NTOK * 8;
;     if (tid <= 128) sBias[tid] = p.rel_bias[t5_bucket(tid * dil) * 40 + g * 8 + head] * 1.4426950408889634f;
.LBB0_493:
	v_writelane_b32 v255, s54, 5
	s_cmp_lt_i32 s23, 2
	s_mov_b64 s[2:3], -1
	v_writelane_b32 v255, s55, 6
	s_cbranch_scc1 .LBB0_764
	s_cmp_gt_i32 s23, 2
	s_cbranch_scc0 .LBB0_552
	v_readlane_b32 s2, v253, 27
	v_readlane_b32 s3, v253, 28
	s_mov_b32 s0, s33
	v_mov_b32_e32 v0, v204
	s_andn2_b64 vcc, exec, s[2:3]
	s_cbranch_vccnz .LBB0_551
	s_mov_b32 s60, s33
	v_readlane_b32 s35, v253, 26
	v_readlane_b32 s44, v254, 14
	v_readlane_b32 s45, v254, 56
	v_readlane_b32 s56, v254, 32
	v_readlane_b32 s57, v254, 33
	v_and_b32_e32 v196, 31, v204
	v_lshrrev_b32_e32 v197, 5, v204
	v_lshl_add_u32 v202, s60, 6, v204
	s_lshl_b32 s0, s60, 5
	v_add_u32_e32 v200, s0, v196
	v_lshlrev_b32_e32 v201, 4, v197
	v_lshlrev_b32_e32 v239, 3, v197
	v_add_u32_e32 v241, 0xffffff80, v202
	v_lshl_add_u32 v203, v202, 1, v214
	v_mul_u32_u24_e32 v198, 0x208, v196
	v_add_u32_e32 v198, v198, v214
	s_lshl_b32 s1, s60, 6
	v_add_u32_e32 v198, s1, v198
	v_add_u32_e32 v209, v198, v239
	v_lshl_add_u32 v198, v196, 2, v214
	v_sub_u32_e32 v198, v198, v201
	v_add_u32_e32 v216, 0x10400, v198
	v_lshl_add_u32 v198, v202, 2, v214
	v_add_u32_e32 v217, 0x10400, v198
	v_add_u32_e32 v198, 0xffffffe1, v202
	v_cmp_gt_u32_e32 vcc, 0x81, v198
	s_mov_b64 s[66:67], vcc
	v_max_i32_e32 v198, 0, v198
	v_min_u32_e32 v198, 0x80, v198
	v_lshlrev_b32_e32 v199, 0, v198
	v_mov_b32_e32 v246, 16
	v_cmp_le_u32_e32 vcc, 22, v199
	s_nop 1
	v_addc_co_u32_e32 v246, vcc, 0, v246, vcc
	v_cmp_le_u32_e32 vcc, 30, v199
	s_nop 1
	v_addc_co_u32_e32 v246, vcc, 0, v246, vcc
	v_cmp_le_u32_e32 vcc, 40, v199
	s_nop 1
	v_addc_co_u32_e32 v246, vcc, 0, v246, vcc
	v_cmp_le_u32_e32 vcc, 54, v199
	s_nop 1
	v_addc_co_u32_e32 v246, vcc, 0, v246, vcc
	v_cmp_le_u32_e32 vcc, 0x49, v199
	s_nop 1
	v_addc_co_u32_e32 v246, vcc, 0, v246, vcc
	v_cmp_le_u32_e32 vcc, 0x63, v199
	s_nop 1
	v_addc_co_u32_e32 v246, vcc, 0, v246, vcc
	v_cmp_le_u32_e32 vcc, 0x86, v199
	s_nop 1
	v_addc_co_u32_e32 v246, vcc, 0, v246, vcc
	v_cmp_le_u32_e32 vcc, 0xb6, v199
	s_nop 1
	v_addc_co_u32_e32 v246, vcc, 0, v246, vcc
	v_cmp_le_u32_e32 vcc, 0xf6, v199
	s_nop 1
	v_addc_co_u32_e32 v246, vcc, 0, v246, vcc
	v_cmp_le_u32_e32 vcc, 0x14c, v199
	s_nop 1
	v_addc_co_u32_e32 v246, vcc, 0, v246, vcc
	v_cmp_le_u32_e32 vcc, 0x1c2, v199
	s_nop 1
	v_addc_co_u32_e32 v246, vcc, 0, v246, vcc
	v_cmp_le_u32_e32 vcc, 0x261, v199
	s_nop 1
	v_addc_co_u32_e32 v246, vcc, 0, v246, vcc
	v_cmp_le_u32_e32 vcc, 0x339, v199
	s_nop 1
	v_addc_co_u32_e32 v246, vcc, 0, v246, vcc
	v_cmp_le_u32_e32 vcc, 0x45d, v199
	s_nop 1
	v_addc_co_u32_e32 v246, vcc, 0, v246, vcc
	v_cmp_le_u32_e32 vcc, 0x5e9, v199
	s_nop 1
	v_addc_co_u32_e32 v246, vcc, 0, v246, vcc
	v_cmp_gt_u32_e32 vcc, 16, v199
	s_nop 1
	v_cndmask_b32_e32 v246, v246, v199, vcc
	v_mul_u32_u24_e32 v218, 0xa0, v246
	v_lshlrev_b32_e32 v199, 2, v198
	v_mov_b32_e32 v246, 16
	v_cmp_le_u32_e32 vcc, 22, v199
	s_nop 1
	v_addc_co_u32_e32 v246, vcc, 0, v246, vcc
	v_cmp_le_u32_e32 vcc, 30, v199
	s_nop 1
	v_addc_co_u32_e32 v246, vcc, 0, v246, vcc
	v_cmp_le_u32_e32 vcc, 40, v199
	s_nop 1
	v_addc_co_u32_e32 v246, vcc, 0, v246, vcc
	v_cmp_le_u32_e32 vcc, 54, v199
	s_nop 1
	v_addc_co_u32_e32 v246, vcc, 0, v246, vcc
	v_cmp_le_u32_e32 vcc, 0x49, v199
	s_nop 1
	v_addc_co_u32_e32 v246, vcc, 0, v246, vcc
	v_cmp_le_u32_e32 vcc, 0x63, v199
	s_nop 1
	v_addc_co_u32_e32 v246, vcc, 0, v246, vcc
	v_cmp_le_u32_e32 vcc, 0x86, v199
	s_nop 1
	v_addc_co_u32_e32 v246, vcc, 0, v246, vcc
	v_cmp_le_u32_e32 vcc, 0xb6, v199
	s_nop 1
	v_addc_co_u32_e32 v246, vcc, 0, v246, vcc
	v_cmp_le_u32_e32 vcc, 0xf6, v199
	s_nop 1
	v_addc_co_u32_e32 v246, vcc, 0, v246, vcc
	v_cmp_le_u32_e32 vcc, 0x14c, v199
	s_nop 1
	v_addc_co_u32_e32 v246, vcc, 0, v246, vcc
	v_cmp_le_u32_e32 vcc, 0x1c2, v199
	s_nop 1
	v_addc_co_u32_e32 v246, vcc, 0, v246, vcc
	v_cmp_le_u32_e32 vcc, 0x261, v199
	s_nop 1
	v_addc_co_u32_e32 v246, vcc, 0, v246, vcc
	v_cmp_le_u32_e32 vcc, 0x339, v199
	s_nop 1
	v_addc_co_u32_e32 v246, vcc, 0, v246, vcc
	v_cmp_le_u32_e32 vcc, 0x45d, v199
	s_nop 1
	v_addc_co_u32_e32 v246, vcc, 0, v246, vcc
	v_cmp_le_u32_e32 vcc, 0x5e9, v199
	s_nop 1
	v_addc_co_u32_e32 v246, vcc, 0, v246, vcc
	v_cmp_gt_u32_e32 vcc, 16, v199
	s_nop 1
	v_cndmask_b32_e32 v246, v246, v199, vcc
	v_mul_u32_u24_e32 v219, 0xa0, v246
	v_lshlrev_b32_e32 v199, 4, v198
	v_mov_b32_e32 v246, 16
	v_cmp_le_u32_e32 vcc, 22, v199
	s_nop 1
	v_addc_co_u32_e32 v246, vcc, 0, v246, vcc
	v_cmp_le_u32_e32 vcc, 30, v199
	s_nop 1
	v_addc_co_u32_e32 v246, vcc, 0, v246, vcc
	v_cmp_le_u32_e32 vcc, 40, v199
	s_nop 1
	v_addc_co_u32_e32 v246, vcc, 0, v246, vcc
	v_cmp_le_u32_e32 vcc, 54, v199
	s_nop 1
	v_addc_co_u32_e32 v246, vcc, 0, v246, vcc
	v_cmp_le_u32_e32 vcc, 0x49, v199
	s_nop 1
	v_addc_co_u32_e32 v246, vcc, 0, v246, vcc
	v_cmp_le_u32_e32 vcc, 0x63, v199
	s_nop 1
	v_addc_co_u32_e32 v246, vcc, 0, v246, vcc
	v_cmp_le_u32_e32 vcc, 0x86, v199
	s_nop 1
	v_addc_co_u32_e32 v246, vcc, 0, v246, vcc
	v_cmp_le_u32_e32 vcc, 0xb6, v199
	s_nop 1
	v_addc_co_u32_e32 v246, vcc, 0, v246, vcc
	v_cmp_le_u32_e32 vcc, 0xf6, v199
	s_nop 1
	v_addc_co_u32_e32 v246, vcc, 0, v246, vcc
	v_cmp_le_u32_e32 vcc, 0x14c, v199
	s_nop 1
	v_addc_co_u32_e32 v246, vcc, 0, v246, vcc
	v_cmp_le_u32_e32 vcc, 0x1c2, v199
	s_nop 1
	v_addc_co_u32_e32 v246, vcc, 0, v246, vcc
	v_cmp_le_u32_e32 vcc, 0x261, v199
	s_nop 1
	v_addc_co_u32_e32 v246, vcc, 0, v246, vcc
	v_cmp_le_u32_e32 vcc, 0x339, v199
	s_nop 1
	v_addc_co_u32_e32 v246, vcc, 0, v246, vcc
	v_cmp_le_u32_e32 vcc, 0x45d, v199
	s_nop 1
	v_addc_co_u32_e32 v246, vcc, 0, v246, vcc
	v_cmp_le_u32_e32 vcc, 0x5e9, v199
	s_nop 1
	v_addc_co_u32_e32 v246, vcc, 0, v246, vcc
	v_cmp_gt_u32_e32 vcc, 16, v199
	s_nop 1
	v_cndmask_b32_e32 v246, v246, v199, vcc
	v_mul_u32_u24_e32 v220, 0xa0, v246
	s_mov_b32 s64, 0
	s_mov_b32 s65, 0
	s_mov_b32 s0, 0
	s_cmp_eq_u32 s45, 0x200
	s_cbranch_scc0 .Lattn_map_old1
	s_lshr_b32 s1, s44, 1
	s_and_b32 s3, s1, 7
	s_lshr_b32 s1, s1, 3
	s_and_b32 s63, s0, 3
	s_lshl_b32 s63, s63, 3
	s_lshr_b32 s68, s1, 3
	s_lshl_b32 s68, s68, 1
	s_add_i32 s63, s63, s68
	s_and_b32 s68, s44, 1
	s_add_i32 s63, s63, s68
	s_lshl_b32 s3, s3, 5
	s_add_i32 s63, s63, s3
	s_mul_i32 s63, s63, 3
	s_lshr_b32 s68, s0, 2
	s_min_u32 s68, s68, 2
	s_add_i32 s63, s63, s68
	s_and_b32 s1, s1, 7
	s_lshl_b32 s0, s63, 3
	s_or_b32 s0, s0, s1
	s_branch .Lattn_map_done1

; DI void phase_attn_a(int wv_, int vb_, int nvb_, char* ws_, const Ctx& p, char* smem) {
;     ...
;   for (int k_ = 0; k_ < (6144 + nvb_ - 1) / nvb_; ++k_) {
;     const int u = (vb_ + k_ * nvb_ < 6144) ? vb_ + k_ * nvb_ : 6143;
;     const int head = u & 7, g = (u >> 3) % 3, rest = u / 24, idx = rest & 31, b = rest >> 5;
.Lattn_loop:
	s_add_i32 s0, s34, 1
	s_cmp_eq_u32 s45, 0x200
	s_cbranch_scc0 .Lattn_map_old2
	s_lshr_b32 s1, s44, 1
	s_and_b32 s3, s1, 7
	s_lshr_b32 s1, s1, 3
	s_and_b32 s63, s0, 3
	s_lshl_b32 s63, s63, 3
	s_lshr_b32 s68, s1, 3
	s_lshl_b32 s68, s68, 1
	s_add_i32 s63, s63, s68
	s_and_b32 s68, s44, 1
	s_add_i32 s63, s63, s68
	s_lshl_b32 s3, s3, 5
	s_add_i32 s63, s63, s3
	s_mul_i32 s63, s63, 3
	s_lshr_b32 s68, s0, 2
	s_min_u32 s68, s68, 2
	s_add_i32 s63, s63, s68
	s_and_b32 s1, s1, 7
	s_lshl_b32 s0, s63, 3
	s_or_b32 s0, s0, s1
	s_branch .Lattn_map_done2
